# grid barrier spin loops keep two generation-word samples in flight (second poll issued before waiting on the first), on top of v34
# baseline (speedup 1.0000x reference)
; __device__ __forceinline__ unsigned xb_ld(unsigned* p)              { return __hip_atomic_load(p, __ATOMIC_RELAXED, __HIP_MEMORY_SCOPE_AGENT); }
; __device__ __forceinline__ unsigned xb_add(unsigned* p, unsigned v) { return __hip_atomic_fetch_add(p, v, __ATOMIC_RELAXED, __HIP_MEMORY_SCOPE_AGENT); }
; #define XB_SPIN(cond, bar) do { unsigned _sp = 0; while (cond) { __builtin_amdgcn_s_sleep(1); \
;     if ((++_sp & 255u) == 0u) { if (xb_ld(&(bar)[XB_TMO])) break; if (_sp > XB_SPIN_CAP) { atomicAdd(&(bar)[XB_TMO], 1u); break; } } } } while (0)
; __device__ __forceinline__ void xcd_barrier(const XcdBarrier& b) {
;     ...
;             const unsigned og = xb_add(&bar[XB_TOP], 1u);
;             const unsigned tg = og / nx;
;             if (og + 1u == (tg + 1u) * nx) xb_add(&bar[XB_TOPGEN], 1u);
;             else XB_SPIN(xb_ld(&bar[XB_TOPGEN]) == tg, bar);
.LBB9_169:
	v_readlane_b32 s4, v254, 45
	v_readlane_b32 s5, v254, 46
	v_cvt_f32_u32_e32 v3, v4
	v_sub_u32_e32 v6, 0, v4
	v_rcp_iflag_f32_e32 v3, v3
	s_nop 1
	global_atomic_add v5, v187, v1, s[4:5] sc0
	v_mul_f32_e32 v3, 0x4f7ffffe, v3
	v_cvt_u32_f32_e32 v3, v3
	v_mul_lo_u32 v6, v6, v3
	v_mul_hi_u32 v6, v3, v6
	v_add_u32_e32 v3, v3, v6
	s_waitcnt vmcnt(0)
	v_mul_hi_u32 v3, v5, v3
	v_mul_lo_u32 v6, v3, v4
	v_sub_u32_e32 v6, v5, v6
	v_add_u32_e32 v7, 1, v3
	v_cmp_ge_u32_e32 vcc, v6, v4
	v_add_u32_e32 v5, 1, v5
	s_nop 0
	v_cndmask_b32_e32 v3, v3, v7, vcc
	v_sub_u32_e32 v7, v6, v4
	v_cndmask_b32_e32 v6, v6, v7, vcc
	v_add_u32_e32 v7, 1, v3
	v_cmp_ge_u32_e32 vcc, v6, v4
	s_nop 1
	v_cndmask_b32_e32 v3, v3, v7, vcc
	v_mul_lo_u32 v6, v4, v3
	v_add_u32_e32 v4, v6, v4
	v_cmp_ne_u32_e32 vcc, v5, v4
	s_and_saveexec_b64 s[4:5], vcc
	s_xor_b64 s[10:11], exec, s[4:5]
	s_cbranch_execz .LBB9_183
	v_readlane_b32 s4, v254, 51
	v_readlane_b32 s5, v254, 52
	s_waitcnt lgkmcnt(0)
	s_nop 3
	global_load_dword v2, v187, s[4:5] sc1
	s_waitcnt vmcnt(0)
	v_cmp_eq_u32_e32 vcc, v2, v3
	s_and_saveexec_b64 s[14:15], vcc
	s_cbranch_execz .LBB9_182
	s_mov_b32 s4, 1
	s_mov_b64 s[18:19], 0
	v_readlane_b32 s22, v254, 51
	v_readlane_b32 s23, v254, 52
	s_nop 4
	global_load_dword v31, v187, s[22:23] sc1
	s_sleep 18
	s_branch .LBB9_173

.LBB9_175:
	v_readlane_b32 s22, v254, 51
	v_readlane_b32 s23, v254, 52
	s_add_i32 s4, s4, 1
	s_mov_b64 s[24:25], -1
	s_nop 1
	s_bitcmp1_b32 s4, 0
	s_cbranch_scc1 .Lpp1_odd
	global_load_dword v30, v187, s[22:23] sc1
	s_waitcnt vmcnt(1)
	v_cmp_ne_u32_e32 vcc, v31, v3
	s_branch .Lpp1_join
.Lpp1_odd:
	global_load_dword v31, v187, s[22:23] sc1
	s_waitcnt vmcnt(1)
	v_cmp_ne_u32_e32 vcc, v30, v3
.Lpp1_join:
	s_orn2_b64 s[22:23], vcc, exec
	s_branch .LBB9_172

; __device__ __forceinline__ unsigned xb_ld(unsigned* p)              { return __hip_atomic_load(p, __ATOMIC_RELAXED, __HIP_MEMORY_SCOPE_AGENT); }
; __device__ __forceinline__ unsigned xb_add(unsigned* p, unsigned v) { return __hip_atomic_fetch_add(p, v, __ATOMIC_RELAXED, __HIP_MEMORY_SCOPE_AGENT); }
; #define XB_SPIN(cond, bar) do { unsigned _sp = 0; while (cond) { __builtin_amdgcn_s_sleep(1); \
;     if ((++_sp & 255u) == 0u) { if (xb_ld(&(bar)[XB_TMO])) break; if (_sp > XB_SPIN_CAP) { atomicAdd(&(bar)[XB_TMO], 1u); break; } } } } while (0)
; __device__ __forceinline__ void xcd_barrier(const XcdBarrier& b) {
;     ...
;             const unsigned og = xb_add(&bar[XB_TOP], 1u);
;             const unsigned tg = og / nx;
;             if (og + 1u == (tg + 1u) * nx) xb_add(&bar[XB_TOPGEN], 1u);
;             else XB_SPIN(xb_ld(&bar[XB_TOPGEN]) == tg, bar);
.LBB9_186:
	s_or_b64 exec, exec, s[14:15]
	s_waitcnt vmcnt(0)
	v_readfirstlane_b32 s4, v4
	v_cvt_f32_u32_e32 v4, v2
	v_sub_u32_e32 v5, 0, v2
	v_add_u32_e32 v3, s4, v3
	v_readlane_b32 s4, v254, 51
	v_rcp_iflag_f32_e32 v4, v4
	v_readlane_b32 s5, v254, 52
	s_mov_b64 s[14:15], -1
	v_mul_f32_e32 v4, 0x4f7ffffe, v4
	v_cvt_u32_f32_e32 v4, v4
	v_mul_lo_u32 v5, v5, v4
	v_mul_hi_u32 v5, v4, v5
	v_add_u32_e32 v4, v4, v5
	v_mul_hi_u32 v4, v3, v4
	v_mul_lo_u32 v5, v4, v2
	v_sub_u32_e32 v5, v3, v5
	v_cmp_ge_u32_e32 vcc, v5, v2
	v_add_u32_e32 v6, 1, v4
	v_add_u32_e32 v3, 1, v3
	v_cndmask_b32_e32 v4, v4, v6, vcc
	v_sub_u32_e32 v6, v5, v2
	v_cndmask_b32_e32 v5, v5, v6, vcc
	v_cmp_ge_u32_e32 vcc, v5, v2
	v_add_u32_e32 v5, 1, v4
	s_nop 0
	v_cndmask_b32_e32 v4, v4, v5, vcc
	v_mul_lo_u32 v5, v2, v4
	v_add_u32_e32 v2, v5, v2
	v_cmp_ne_u32_e32 vcc, v3, v2
	v_mov_b64_e32 v[2:3], s[4:5]
	s_and_saveexec_b64 s[10:11], vcc
	s_cbranch_execz .LBB9_198
	v_readlane_b32 s4, v254, 51
	v_readlane_b32 s5, v254, 52
	s_mov_b64 s[18:19], 0
	s_nop 3
	global_load_dword v2, v187, s[4:5] sc1
	s_waitcnt vmcnt(0)
	v_cmp_eq_u32_e32 vcc, v2, v4
	s_and_saveexec_b64 s[14:15], vcc
	s_cbranch_execz .LBB9_197
	s_mov_b32 s4, 1
	v_readlane_b32 s22, v254, 51
	v_readlane_b32 s23, v254, 52
	s_nop 4
	global_load_dword v31, v187, s[22:23] sc1
	s_sleep 18
	s_branch .LBB9_190

.LBB9_192:
	v_readlane_b32 s22, v254, 51
	v_readlane_b32 s23, v254, 52
	s_add_i32 s4, s4, 1
	s_mov_b64 s[24:25], -1
	s_nop 1
	s_bitcmp1_b32 s4, 0
	s_cbranch_scc1 .Lpp2_odd
	global_load_dword v30, v187, s[22:23] sc1
	s_waitcnt vmcnt(1)
	v_cmp_ne_u32_e32 vcc, v31, v4
	s_branch .Lpp2_join
.Lpp2_odd:
	global_load_dword v31, v187, s[22:23] sc1
	s_waitcnt vmcnt(1)
	v_cmp_ne_u32_e32 vcc, v30, v4

; __device__ __forceinline__ unsigned xb_ld(unsigned* p)              { return __hip_atomic_load(p, __ATOMIC_RELAXED, __HIP_MEMORY_SCOPE_AGENT); }
; __device__ __forceinline__ unsigned xb_add(unsigned* p, unsigned v) { return __hip_atomic_fetch_add(p, v, __ATOMIC_RELAXED, __HIP_MEMORY_SCOPE_AGENT); }
; #define XB_SPIN(cond, bar) do { unsigned _sp = 0; while (cond) { __builtin_amdgcn_s_sleep(1); \
;     if ((++_sp & 255u) == 0u) { if (xb_ld(&(bar)[XB_TMO])) break; if (_sp > XB_SPIN_CAP) { atomicAdd(&(bar)[XB_TMO], 1u); break; } } } } while (0)
; __device__ __forceinline__ void xcd_barrier(const XcdBarrier& b) {
;     ...
;             const unsigned og = xb_add(&bar[XB_TOP], 1u);
;             const unsigned tg = og / nx;
;             if (og + 1u == (tg + 1u) * nx) xb_add(&bar[XB_TOPGEN], 1u);
;             else XB_SPIN(xb_ld(&bar[XB_TOPGEN]) == tg, bar);
.LBB9_1027:
	s_or_b64 exec, exec, s[14:15]
	s_waitcnt vmcnt(0)
	v_readfirstlane_b32 s3, v4
	v_cvt_f32_u32_e32 v4, v2
	v_sub_u32_e32 v5, 0, v2
	v_add_u32_e32 v3, s3, v3
	v_readlane_b32 s4, v254, 51
	v_rcp_iflag_f32_e32 v4, v4
	v_readlane_b32 s5, v254, 52
	s_mov_b64 s[14:15], -1
	v_mul_f32_e32 v4, 0x4f7ffffe, v4
	v_cvt_u32_f32_e32 v4, v4
	v_mul_lo_u32 v5, v5, v4
	v_mul_hi_u32 v5, v4, v5
	v_add_u32_e32 v4, v4, v5
	v_mul_hi_u32 v4, v3, v4
	v_mul_lo_u32 v5, v4, v2
	v_sub_u32_e32 v5, v3, v5
	v_cmp_ge_u32_e32 vcc, v5, v2
	v_add_u32_e32 v6, 1, v4
	v_add_u32_e32 v3, 1, v3
	v_cndmask_b32_e32 v4, v4, v6, vcc
	v_sub_u32_e32 v6, v5, v2
	v_cndmask_b32_e32 v5, v5, v6, vcc
	v_cmp_ge_u32_e32 vcc, v5, v2
	v_add_u32_e32 v5, 1, v4
	s_nop 0
	v_cndmask_b32_e32 v4, v4, v5, vcc
	v_mul_lo_u32 v5, v2, v4
	v_add_u32_e32 v2, v5, v2
	v_cmp_ne_u32_e32 vcc, v3, v2
	v_mov_b64_e32 v[2:3], s[4:5]
	s_and_saveexec_b64 s[10:11], vcc
	s_cbranch_execz .LBB9_1039
	v_readlane_b32 s4, v254, 51
	v_readlane_b32 s5, v254, 52
	s_mov_b64 s[18:19], 0
	s_nop 3
	global_load_dword v2, v187, s[4:5] sc1
	s_waitcnt vmcnt(0)
	v_cmp_eq_u32_e32 vcc, v2, v4
	s_and_saveexec_b64 s[14:15], vcc
	s_cbranch_execz .LBB9_1038
	s_mov_b32 s4, 1
	v_readlane_b32 s22, v254, 51
	v_readlane_b32 s23, v254, 52
	s_nop 4
	global_load_dword v31, v187, s[22:23] sc1
	s_sleep 18
	s_branch .LBB9_1031

; __device__ __forceinline__ unsigned xb_ld(unsigned* p)              { return __hip_atomic_load(p, __ATOMIC_RELAXED, __HIP_MEMORY_SCOPE_AGENT); }
; __device__ __forceinline__ unsigned xb_add(unsigned* p, unsigned v) { return __hip_atomic_fetch_add(p, v, __ATOMIC_RELAXED, __HIP_MEMORY_SCOPE_AGENT); }
; #define XB_SPIN(cond, bar) do { unsigned _sp = 0; while (cond) { __builtin_amdgcn_s_sleep(1); \
;     if ((++_sp & 255u) == 0u) { if (xb_ld(&(bar)[XB_TMO])) break; if (_sp > XB_SPIN_CAP) { atomicAdd(&(bar)[XB_TMO], 1u); break; } } } } while (0)
; __device__ __forceinline__ void xcd_barrier(const XcdBarrier& b) {
;     ...
;             const unsigned og = xb_add(&bar[XB_TOP], 1u);
;             const unsigned tg = og / nx;
;             if (og + 1u == (tg + 1u) * nx) xb_add(&bar[XB_TOPGEN], 1u);
;             else XB_SPIN(xb_ld(&bar[XB_TOPGEN]) == tg, bar);
.LBB9_1689:
	v_readlane_b32 s4, v254, 45
	v_readlane_b32 s5, v254, 46
	v_cvt_f32_u32_e32 v3, v4
	v_sub_u32_e32 v6, 0, v4
	v_rcp_iflag_f32_e32 v3, v3
	s_nop 1
	global_atomic_add v5, v187, v1, s[4:5] sc0
	v_mul_f32_e32 v3, 0x4f7ffffe, v3
	v_cvt_u32_f32_e32 v3, v3
	v_mul_lo_u32 v6, v6, v3
	v_mul_hi_u32 v6, v3, v6
	v_add_u32_e32 v3, v3, v6
	s_waitcnt vmcnt(0)
	v_mul_hi_u32 v3, v5, v3
	v_mul_lo_u32 v6, v3, v4
	v_sub_u32_e32 v6, v5, v6
	v_add_u32_e32 v7, 1, v3
	v_cmp_ge_u32_e32 vcc, v6, v4
	v_add_u32_e32 v5, 1, v5
	s_nop 0
	v_cndmask_b32_e32 v3, v3, v7, vcc
	v_sub_u32_e32 v7, v6, v4
	v_cndmask_b32_e32 v6, v6, v7, vcc
	v_add_u32_e32 v7, 1, v3
	v_cmp_ge_u32_e32 vcc, v6, v4
	s_nop 1
	v_cndmask_b32_e32 v3, v3, v7, vcc
	v_mul_lo_u32 v6, v4, v3
	v_add_u32_e32 v4, v6, v4
	v_cmp_ne_u32_e32 vcc, v5, v4
	s_and_saveexec_b64 s[4:5], vcc
	s_xor_b64 s[14:15], exec, s[4:5]
	s_cbranch_execz .LBB9_1703
	v_readlane_b32 s4, v254, 51
	v_readlane_b32 s5, v254, 52
	s_waitcnt lgkmcnt(0)
	s_nop 3
	global_load_dword v2, v187, s[4:5] sc1
	s_waitcnt vmcnt(0)
	v_cmp_eq_u32_e32 vcc, v2, v3
	s_and_saveexec_b64 s[18:19], vcc
	s_cbranch_execz .LBB9_1702
	s_mov_b32 s4, 1
	s_mov_b64 s[20:21], 0
	v_readlane_b32 s24, v254, 51
	v_readlane_b32 s25, v254, 52
	s_nop 4
	global_load_dword v31, v187, s[24:25] sc1
	s_sleep 18
	s_branch .LBB9_1693

.LBB9_1695:
	v_readlane_b32 s24, v254, 51
	v_readlane_b32 s25, v254, 52
	s_add_i32 s4, s4, 1
	s_mov_b64 s[26:27], -1
	s_nop 1
	s_bitcmp1_b32 s4, 0
	s_cbranch_scc1 .Lpp21_odd
	global_load_dword v30, v187, s[24:25] sc1
	s_waitcnt vmcnt(1)
	v_cmp_ne_u32_e32 vcc, v31, v3
	s_branch .Lpp21_join
.Lpp21_odd:
	global_load_dword v31, v187, s[24:25] sc1
	s_waitcnt vmcnt(1)
	v_cmp_ne_u32_e32 vcc, v30, v3
.Lpp21_join:
	s_orn2_b64 s[24:25], vcc, exec
	s_branch .LBB9_1692

; __device__ __forceinline__ unsigned xb_ld(unsigned* p)              { return __hip_atomic_load(p, __ATOMIC_RELAXED, __HIP_MEMORY_SCOPE_AGENT); }
; __device__ __forceinline__ unsigned xb_add(unsigned* p, unsigned v) { return __hip_atomic_fetch_add(p, v, __ATOMIC_RELAXED, __HIP_MEMORY_SCOPE_AGENT); }
; #define XB_SPIN(cond, bar) do { unsigned _sp = 0; while (cond) { __builtin_amdgcn_s_sleep(1); \
;     if ((++_sp & 255u) == 0u) { if (xb_ld(&(bar)[XB_TMO])) break; if (_sp > XB_SPIN_CAP) { atomicAdd(&(bar)[XB_TMO], 1u); break; } } } } while (0)
; __device__ __forceinline__ void xcd_barrier(const XcdBarrier& b) {
;     ...
;             const unsigned og = xb_add(&bar[XB_TOP], 1u);
;             const unsigned tg = og / nx;
;             if (og + 1u == (tg + 1u) * nx) xb_add(&bar[XB_TOPGEN], 1u);
;             else XB_SPIN(xb_ld(&bar[XB_TOPGEN]) == tg, bar);
.LBB9_1706:
	s_or_b64 exec, exec, s[18:19]
	s_waitcnt vmcnt(0)
	v_readfirstlane_b32 s3, v4
	v_cvt_f32_u32_e32 v4, v2
	v_sub_u32_e32 v5, 0, v2
	v_add_u32_e32 v3, s3, v3
	v_readlane_b32 s4, v254, 51
	v_rcp_iflag_f32_e32 v4, v4
	v_readlane_b32 s5, v254, 52
	s_mov_b64 s[18:19], -1
	v_mul_f32_e32 v4, 0x4f7ffffe, v4
	v_cvt_u32_f32_e32 v4, v4
	v_mul_lo_u32 v5, v5, v4
	v_mul_hi_u32 v5, v4, v5
	v_add_u32_e32 v4, v4, v5
	v_mul_hi_u32 v4, v3, v4
	v_mul_lo_u32 v5, v4, v2
	v_sub_u32_e32 v5, v3, v5
	v_cmp_ge_u32_e32 vcc, v5, v2
	v_add_u32_e32 v6, 1, v4
	v_add_u32_e32 v3, 1, v3
	v_cndmask_b32_e32 v4, v4, v6, vcc
	v_sub_u32_e32 v6, v5, v2
	v_cndmask_b32_e32 v5, v5, v6, vcc
	v_cmp_ge_u32_e32 vcc, v5, v2
	v_add_u32_e32 v5, 1, v4
	s_nop 0
	v_cndmask_b32_e32 v4, v4, v5, vcc
	v_mul_lo_u32 v5, v2, v4
	v_add_u32_e32 v2, v5, v2
	v_cmp_ne_u32_e32 vcc, v3, v2
	v_mov_b64_e32 v[2:3], s[4:5]
	s_and_saveexec_b64 s[14:15], vcc
	s_cbranch_execz .LBB9_1718
	v_readlane_b32 s4, v254, 51
	v_readlane_b32 s5, v254, 52
	s_mov_b64 s[20:21], 0
	s_nop 3
	global_load_dword v2, v187, s[4:5] sc1
	s_waitcnt vmcnt(0)
	v_cmp_eq_u32_e32 vcc, v2, v4
	s_and_saveexec_b64 s[18:19], vcc
	s_cbranch_execz .LBB9_1717
	s_mov_b32 s4, 1
	v_readlane_b32 s24, v254, 51
	v_readlane_b32 s25, v254, 52
	s_nop 4
	global_load_dword v31, v187, s[24:25] sc1
	s_sleep 18
	s_branch .LBB9_1710

.LBB9_1712:
	v_readlane_b32 s24, v254, 51
	v_readlane_b32 s25, v254, 52
	s_add_i32 s4, s4, 1
	s_mov_b64 s[26:27], -1
	s_nop 1
	s_bitcmp1_b32 s4, 0
	s_cbranch_scc1 .Lpp22_odd
	global_load_dword v30, v187, s[24:25] sc1
	s_waitcnt vmcnt(1)
	v_cmp_ne_u32_e32 vcc, v31, v4
	s_branch .Lpp22_join
.Lpp22_odd:
	global_load_dword v31, v187, s[24:25] sc1
	s_waitcnt vmcnt(1)
	v_cmp_ne_u32_e32 vcc, v30, v4
